# comb2 + J1: PV step head - first V-fragment ds_read group issued ahead of the rescale-flag read/test/branch chain
# speedup vs baseline: 1.0128x; 1.0128x over previous
; __device__ __forceinline__ int crow(int r, int hi) { return (r & 3) + 8 * (r >> 2) + 4 * hi; }
; __device__ __forceinline__ void attn2_block(const Blk& c, char* lds) {
;     ...
;             if (s >= 1) {
;                 const int par = (s - 1) & 1;
;                 const unsigned fl = (unsigned)__builtin_amdgcn_readfirstlane((int)FLb[par]);
;                 if (fl) {
; #pragma unroll
;                     for (int r = 0; r < 16; ++r) { const float a = ALb[par * 32 + att::crow(r, hi)];
; #pragma unroll
;                         for (int d_ = 0; d_ < 8; ++d_) o[d_][r] *= a; } }
;                 const char* pr = Pb + par * 4096 + lane * 16;
.LBB0_546:
	s_andn2_b32 s85, 1, s85
	v_lshl_add_u32 v176, s85, 15, v231
	ds_read_b64_tr_b16 v[232:233], v176 offset:0
	ds_read_b64_tr_b16 v[234:235], v176 offset:2048
	ds_read_b64_tr_b16 v[242:243], v176 offset:4096
	ds_read_b64_tr_b16 v[244:245], v176 offset:6144
	ds_read_b64_tr_b16 v[246:247], v176 offset:8192
	ds_read_b64_tr_b16 v[248:249], v176 offset:10240
	ds_read_b64_tr_b16 v[250:251], v176 offset:12288
	ds_read_b64_tr_b16 v[252:253], v176 offset:14336
	s_lshl_b32 s10, s85, 2
	s_add_i32 s10, s79, s10
	v_mov_b32_e32 v2, s10
	ds_read_b32 v2, v2
	s_waitcnt lgkmcnt(0)
	v_readfirstlane_b32 s10, v2
	s_cmp_eq_u32 s10, 0
	s_cbranch_scc1 .LBB0_548
	v_lshl_add_u32 v2, s85, 7, v212
	ds_read_b128 v[192:195], v2 offset:96
	ds_read_b128 v[188:191], v2 offset:64
	ds_read_b128 v[184:187], v2 offset:32
	ds_read_b128 v[180:183], v2
	s_waitcnt lgkmcnt(3)
	v_pk_mul_f32 v[130:131], v[130:131], v[194:195]
	s_waitcnt lgkmcnt(2)
	v_pk_mul_f32 v[126:127], v[126:127], v[190:191]
	s_waitcnt lgkmcnt(1)
	v_pk_mul_f32 v[122:123], v[122:123], v[186:187]
	s_waitcnt lgkmcnt(0)
	v_pk_mul_f32 v[118:119], v[118:119], v[182:183]
	v_pk_mul_f32 v[128:129], v[128:129], v[192:193]
	v_pk_mul_f32 v[124:125], v[124:125], v[188:189]
	v_pk_mul_f32 v[120:121], v[120:121], v[184:185]
	v_pk_mul_f32 v[116:117], v[116:117], v[180:181]
	v_pk_mul_f32 v[114:115], v[114:115], v[194:195]
	v_pk_mul_f32 v[110:111], v[110:111], v[190:191]
	v_pk_mul_f32 v[106:107], v[106:107], v[186:187]
	v_pk_mul_f32 v[102:103], v[102:103], v[182:183]
	v_pk_mul_f32 v[112:113], v[112:113], v[192:193]
	v_pk_mul_f32 v[108:109], v[108:109], v[188:189]
	v_pk_mul_f32 v[104:105], v[104:105], v[184:185]
	v_pk_mul_f32 v[100:101], v[100:101], v[180:181]
	v_pk_mul_f32 v[98:99], v[98:99], v[194:195]
	v_pk_mul_f32 v[94:95], v[94:95], v[190:191]
	v_pk_mul_f32 v[90:91], v[90:91], v[186:187]
	v_pk_mul_f32 v[86:87], v[86:87], v[182:183]
	v_pk_mul_f32 v[96:97], v[96:97], v[192:193]
	v_pk_mul_f32 v[92:93], v[92:93], v[188:189]
	v_pk_mul_f32 v[88:89], v[88:89], v[184:185]
	v_pk_mul_f32 v[84:85], v[84:85], v[180:181]
	v_pk_mul_f32 v[82:83], v[82:83], v[194:195]
	v_pk_mul_f32 v[78:79], v[78:79], v[190:191]
	v_pk_mul_f32 v[74:75], v[74:75], v[186:187]
	v_pk_mul_f32 v[70:71], v[70:71], v[182:183]
	v_pk_mul_f32 v[80:81], v[80:81], v[192:193]
	v_pk_mul_f32 v[76:77], v[76:77], v[188:189]
	v_pk_mul_f32 v[72:73], v[72:73], v[184:185]
	v_pk_mul_f32 v[68:69], v[68:69], v[180:181]
	v_pk_mul_f32 v[66:67], v[66:67], v[194:195]
	v_pk_mul_f32 v[62:63], v[62:63], v[190:191]
	v_pk_mul_f32 v[58:59], v[58:59], v[186:187]
	v_pk_mul_f32 v[54:55], v[54:55], v[182:183]
	v_pk_mul_f32 v[64:65], v[64:65], v[192:193]
	v_pk_mul_f32 v[60:61], v[60:61], v[188:189]
	v_pk_mul_f32 v[56:57], v[56:57], v[184:185]
	v_pk_mul_f32 v[52:53], v[52:53], v[180:181]
	v_pk_mul_f32 v[50:51], v[50:51], v[194:195]
	v_pk_mul_f32 v[46:47], v[46:47], v[190:191]
	v_pk_mul_f32 v[42:43], v[42:43], v[186:187]
	v_pk_mul_f32 v[38:39], v[38:39], v[182:183]
	v_pk_mul_f32 v[48:49], v[48:49], v[192:193]
	v_pk_mul_f32 v[44:45], v[44:45], v[188:189]
	v_pk_mul_f32 v[40:41], v[40:41], v[184:185]
	v_pk_mul_f32 v[36:37], v[36:37], v[180:181]
	v_pk_mul_f32 v[34:35], v[34:35], v[194:195]
	v_pk_mul_f32 v[30:31], v[30:31], v[190:191]
	v_pk_mul_f32 v[26:27], v[26:27], v[186:187]
	v_pk_mul_f32 v[22:23], v[22:23], v[182:183]
	v_pk_mul_f32 v[32:33], v[32:33], v[192:193]
	v_pk_mul_f32 v[28:29], v[28:29], v[188:189]
	v_pk_mul_f32 v[24:25], v[24:25], v[184:185]
	v_pk_mul_f32 v[20:21], v[20:21], v[180:181]
	v_pk_mul_f32 v[18:19], v[18:19], v[194:195]
	v_pk_mul_f32 v[14:15], v[14:15], v[190:191]
	v_pk_mul_f32 v[10:11], v[10:11], v[186:187]
	v_pk_mul_f32 v[6:7], v[6:7], v[182:183]
	v_pk_mul_f32 v[16:17], v[16:17], v[192:193]
	v_pk_mul_f32 v[12:13], v[12:13], v[188:189]
	v_pk_mul_f32 v[8:9], v[8:9], v[184:185]
	v_pk_mul_f32 v[4:5], v[4:5], v[180:181]
; #define A2_WRITET(buf) do { char* kd_ = lds + L_K + (buf) * SHM_K; char* vd_ = lds + L_V + (buf) * 2 * SHM_V; \
;         *(bf16x8*)(kd_ + kws) = sk0; *(bf16x8*)(kd_ + kws + 32 * 256) = sk1; *(bf16x8*)(vd_ + vst0) = sv00; *(bf16x8*)(vd_ + vst1) = sv01; *(bf16x8*)(vd_ + SHM_V + vst0) = sv10; *(bf16x8*)(vd_ + SHM_V + vst1) = sv11; } while (0)
; __device__ __forceinline__ void attn2_block(const Blk& c, char* lds) {
;     ...
;                 const char* pr = Pb + par * 4096 + lane * 16;
;                 const bf16x8 pa0 = *(const bf16x8*)(pr), pa1 = *(const bf16x8*)(pr + 1024), pa2 = *(const bf16x8*)(pr + 2048), pa3 = *(const bf16x8*)(pr + 3072);
;                 const int vb = vbase + par * 2 * SHM_V;
;                 att::pv_tile<0>(o, vb, pa0, pa1, pa2, pa3);
;                 att::pv_tile<0>(o + 4, vb + SHM_V, pa0, pa1, pa2, pa3);
;             }
;             __syncthreads();
;             if (s + 1 < NT) { asm volatile("s_waitcnt vmcnt(0)" ::: "memory"); A2_WRITET((s + 1) & 1); }
;             __syncthreads();
.LBB0_548:
	v_lshl_add_u32 v2, s85, 12, v230
	ds_read_b128 v[192:195], v2
	ds_read_b128 v[188:191], v2 offset:1024
	ds_read_b128 v[184:187], v2 offset:2048
	ds_read_b128 v[180:183], v2 offset:3072
	v_lshl_add_u32 v2, s85, 15, v231
	s_waitcnt lgkmcnt(3)
	s_waitcnt lgkmcnt(3)
	v_mfma_f32_32x32x16_bf16 v[116:131], v[192:195], v[232:235], v[116:131]
	ds_read_b64_tr_b16 v[232:233], v2 offset:0x200
	ds_read_b64_tr_b16 v[234:235], v2 offset:0xa00
	s_waitcnt lgkmcnt(4)
	v_mfma_f32_32x32x16_bf16 v[116:131], v[188:191], v[242:245], v[116:131]
	ds_read_b64_tr_b16 v[242:243], v2 offset:0x1200
	ds_read_b64_tr_b16 v[244:245], v2 offset:0x1a00
	s_waitcnt lgkmcnt(5)
	v_mfma_f32_32x32x16_bf16 v[116:131], v[184:187], v[246:249], v[116:131]
	ds_read_b64_tr_b16 v[246:247], v2 offset:0x2200
	ds_read_b64_tr_b16 v[248:249], v2 offset:0x2a00
	s_waitcnt lgkmcnt(6)
	v_mfma_f32_32x32x16_bf16 v[116:131], v[180:183], v[250:253], v[116:131]
	ds_read_b64_tr_b16 v[250:251], v2 offset:0x3200
	ds_read_b64_tr_b16 v[252:253], v2 offset:0x3a00
	s_waitcnt lgkmcnt(6)
	v_mfma_f32_32x32x16_bf16 v[100:115], v[192:195], v[232:235], v[100:115]
	ds_read_b64_tr_b16 v[232:233], v2 offset:0x400
	ds_read_b64_tr_b16 v[234:235], v2 offset:0xc00
	s_waitcnt lgkmcnt(6)
	v_mfma_f32_32x32x16_bf16 v[100:115], v[188:191], v[242:245], v[100:115]
	ds_read_b64_tr_b16 v[242:243], v2 offset:0x1400
	ds_read_b64_tr_b16 v[244:245], v2 offset:0x1c00
	s_waitcnt lgkmcnt(6)
	v_mfma_f32_32x32x16_bf16 v[100:115], v[184:187], v[246:249], v[100:115]
	ds_read_b64_tr_b16 v[246:247], v2 offset:0x2400
	ds_read_b64_tr_b16 v[248:249], v2 offset:0x2c00
	s_waitcnt lgkmcnt(6)
	v_mfma_f32_32x32x16_bf16 v[100:115], v[180:183], v[250:253], v[100:115]
	ds_read_b64_tr_b16 v[250:251], v2 offset:0x3400
	ds_read_b64_tr_b16 v[252:253], v2 offset:0x3c00
	s_waitcnt lgkmcnt(6)
	v_mfma_f32_32x32x16_bf16 v[84:99], v[192:195], v[232:235], v[84:99]
	ds_read_b64_tr_b16 v[232:233], v2 offset:0x600
	ds_read_b64_tr_b16 v[234:235], v2 offset:0xe00
	s_waitcnt lgkmcnt(6)
	v_mfma_f32_32x32x16_bf16 v[84:99], v[188:191], v[242:245], v[84:99]
	ds_read_b64_tr_b16 v[242:243], v2 offset:0x1600
	ds_read_b64_tr_b16 v[244:245], v2 offset:0x1e00
	s_waitcnt lgkmcnt(6)
	v_mfma_f32_32x32x16_bf16 v[84:99], v[184:187], v[246:249], v[84:99]
	ds_read_b64_tr_b16 v[246:247], v2 offset:0x2600
	ds_read_b64_tr_b16 v[248:249], v2 offset:0x2e00
	s_waitcnt lgkmcnt(6)
	v_mfma_f32_32x32x16_bf16 v[84:99], v[180:183], v[250:253], v[84:99]
	ds_read_b64_tr_b16 v[250:251], v2 offset:0x3600
	ds_read_b64_tr_b16 v[252:253], v2 offset:0x3e00
	s_waitcnt lgkmcnt(6)
	v_mfma_f32_32x32x16_bf16 v[68:83], v[192:195], v[232:235], v[68:83]
	v_add_u32_e32 v2, 0x4000, v2
	ds_read_b64_tr_b16 v[232:233], v2 offset:0
	ds_read_b64_tr_b16 v[234:235], v2 offset:0x800
	s_waitcnt lgkmcnt(6)
	v_mfma_f32_32x32x16_bf16 v[68:83], v[188:191], v[242:245], v[68:83]
	ds_read_b64_tr_b16 v[242:243], v2 offset:0x1000
	ds_read_b64_tr_b16 v[244:245], v2 offset:0x1800
	s_waitcnt lgkmcnt(6)
	v_mfma_f32_32x32x16_bf16 v[68:83], v[184:187], v[246:249], v[68:83]
	ds_read_b64_tr_b16 v[246:247], v2 offset:0x2000
	ds_read_b64_tr_b16 v[248:249], v2 offset:0x2800
	s_waitcnt lgkmcnt(6)
	v_mfma_f32_32x32x16_bf16 v[68:83], v[180:183], v[250:253], v[68:83]
	ds_read_b64_tr_b16 v[250:251], v2 offset:0x3000
	ds_read_b64_tr_b16 v[252:253], v2 offset:0x3800
	s_waitcnt lgkmcnt(6)
	v_mfma_f32_32x32x16_bf16 v[52:67], v[192:195], v[232:235], v[52:67]
	ds_read_b64_tr_b16 v[232:233], v2 offset:0x200
	ds_read_b64_tr_b16 v[234:235], v2 offset:0xa00
	s_waitcnt lgkmcnt(6)
	v_mfma_f32_32x32x16_bf16 v[52:67], v[188:191], v[242:245], v[52:67]
	ds_read_b64_tr_b16 v[242:243], v2 offset:0x1200
	ds_read_b64_tr_b16 v[244:245], v2 offset:0x1a00
	s_waitcnt lgkmcnt(6)
	v_mfma_f32_32x32x16_bf16 v[52:67], v[184:187], v[246:249], v[52:67]
	ds_read_b64_tr_b16 v[246:247], v2 offset:0x2200
	ds_read_b64_tr_b16 v[248:249], v2 offset:0x2a00
	s_waitcnt lgkmcnt(6)
	v_mfma_f32_32x32x16_bf16 v[52:67], v[180:183], v[250:253], v[52:67]
	ds_read_b64_tr_b16 v[250:251], v2 offset:0x3200
	ds_read_b64_tr_b16 v[252:253], v2 offset:0x3a00
	s_waitcnt lgkmcnt(6)
	v_mfma_f32_32x32x16_bf16 v[36:51], v[192:195], v[232:235], v[36:51]
	ds_read_b64_tr_b16 v[232:233], v2 offset:0x400
	ds_read_b64_tr_b16 v[234:235], v2 offset:0xc00
	s_waitcnt lgkmcnt(6)
	v_mfma_f32_32x32x16_bf16 v[36:51], v[188:191], v[242:245], v[36:51]
	ds_read_b64_tr_b16 v[242:243], v2 offset:0x1400
	ds_read_b64_tr_b16 v[244:245], v2 offset:0x1c00
	s_waitcnt lgkmcnt(6)
	v_mfma_f32_32x32x16_bf16 v[36:51], v[184:187], v[246:249], v[36:51]
	ds_read_b64_tr_b16 v[246:247], v2 offset:0x2400
	ds_read_b64_tr_b16 v[248:249], v2 offset:0x2c00
	s_waitcnt lgkmcnt(6)
	v_mfma_f32_32x32x16_bf16 v[36:51], v[180:183], v[250:253], v[36:51]
	ds_read_b64_tr_b16 v[250:251], v2 offset:0x3400
	ds_read_b64_tr_b16 v[252:253], v2 offset:0x3c00
	s_waitcnt lgkmcnt(6)
	v_mfma_f32_32x32x16_bf16 v[20:35], v[192:195], v[232:235], v[20:35]
	ds_read_b64_tr_b16 v[232:233], v2 offset:0x600
	ds_read_b64_tr_b16 v[234:235], v2 offset:0xe00
	s_waitcnt lgkmcnt(6)
	v_mfma_f32_32x32x16_bf16 v[20:35], v[188:191], v[242:245], v[20:35]
	ds_read_b64_tr_b16 v[242:243], v2 offset:0x1600
	ds_read_b64_tr_b16 v[244:245], v2 offset:0x1e00
	s_waitcnt lgkmcnt(6)
	v_mfma_f32_32x32x16_bf16 v[20:35], v[184:187], v[246:249], v[20:35]
	ds_read_b64_tr_b16 v[246:247], v2 offset:0x2600
	ds_read_b64_tr_b16 v[248:249], v2 offset:0x2e00
	s_waitcnt lgkmcnt(6)
	v_mfma_f32_32x32x16_bf16 v[20:35], v[180:183], v[250:253], v[20:35]
	ds_read_b64_tr_b16 v[250:251], v2 offset:0x3600
	ds_read_b64_tr_b16 v[252:253], v2 offset:0x3e00
	s_waitcnt lgkmcnt(0)
	v_mfma_f32_32x32x16_bf16 v[4:19], v[192:195], v[232:235], v[4:19]
	s_waitcnt vmcnt(0)
	s_barrier
	v_mfma_f32_32x32x16_bf16 v[4:19], v[188:191], v[242:245], v[4:19]
	v_mfma_f32_32x32x16_bf16 v[4:19], v[184:187], v[246:249], v[4:19]
	v_mfma_f32_32x32x16_bf16 v[4:19], v[180:183], v[250:253], v[4:19]
	s_branch .LBB0_543
